# v38 + token pass touches the cache lines of its later stages (rest of the ZA row, three ZL rows) at the row top
# baseline (speedup 1.0000x reference)
; __device__ __forceinline__ float bflo(unsigned w) { return __uint_as_float(w << 16); }
; __device__ __forceinline__ float bfhi(unsigned w) { return __uint_as_float(w & 0xffff0000u); }
; __device__ __forceinline__ unsigned pkbf(float lo, float hi) { return pg8::cvt_pk_bf16(lo, hi); }
; __device__ __forceinline__ void p5_row(const P& p, int row, int lane) {
;     unsigned char* ws = p.ws;
;     bf16_t* za = (bf16_t*)(ws + WS_ZA) + (size_t)row * 768;
;     { unsigned* q = (unsigned*)(za + lane * 6); const unsigned w0 = q[0], w1 = q[1], w2 = q[2];
;       float f[6] = {bflo(w0), bfhi(w0), bflo(w1), bfhi(w1), bflo(w2), bfhi(w2)}; float s = 0.f;
; #pragma unroll
;       for (int e = 0; e < 6; ++e) s += f[e] * f[e];
;       const float rstd = 1.0f / sqrtf(wave_sum(s) * (1.f / 384.f) + NORM_EPS); const float* g = p.in[8] + lane * 6;
; #pragma unroll
;       for (int e = 0; e < 6; ++e) f[e] = f[e] * rstd * g[e];
;       q[0] = pkbf(f[0], f[1]); q[1] = pkbf(f[2], f[3]); q[2] = pkbf(f[4], f[5]); }
;     { unsigned* q = (unsigned*)(za + 384 + lane * 4); const unsigned w0 = q[0], w1 = q[1];
;       float f[4] = {bflo(w0), bfhi(w0), bflo(w1), bfhi(w1)}; float s = 0.f;
; #pragma unroll
;       for (int e = 0; e < 4; ++e) s += f[e] * f[e];
;       const float rstd = 1.0f / sqrtf(wave_sum(s) * (1.f / 256.f) + NORM_EPS); const float* g = p.in[10] + lane * 4;
; #pragma unroll
;       for (int e = 0; e < 4; ++e) f[e] = f[e] * rstd * g[e];
;       q[0] = pkbf(f[0], f[1]); q[1] = pkbf(f[2], f[3]); }
;     if (lane < 16) { const float x1 = __uint_as_float((unsigned)za[640 + lane] << 16), x2 = __uint_as_float((unsigned)za[656 + lane] << 16);
;       const float* rp = (const float*)(ws + WS_ROPE) + ((size_t)seq_pos(row) * 16 + lane) * 2; const float c = rp[0], s = rp[1];
;       const unsigned w = pkbf(x1 * c - x2 * s, x1 * s + x2 * c);
;       unsigned* kr = (unsigned*)((bf16_t*)((unsigned char*)p.out + DO_K) + (size_t)row * 768 + 64) + lane;
; #pragma unroll
;       for (int h = 0; h < NH; ++h) kr[h * 48] = w; }
.LBB0_419:
	v_lshl_add_u64 v[0:1], s[50:51], 0, v[26:27]
	v_add_co_u32_e32 v4, vcc, 0x12000000, v0
	s_nop 1
	v_addc_co_u32_e32 v5, vcc, 0, v1, vcc
	global_load_dwordx3 v[0:2], v[4:5], off
	global_load_dwordx3 v[192:194], v[4:5], off offset:768
	v_lshl_add_u64 v[216:217], s[50:51], 0, v[22:23]
	s_mov_b64 s[98:99], 0x16800000
	v_lshl_add_u64 v[216:217], v[216:217], 0, s[98:99]
	global_load_dwordx3 v[196:198], v[216:217], off
	global_load_dwordx3 v[200:202], v[216:217], off offset:1024
	global_load_dwordx3 v[204:206], v[216:217], off offset:-1024
	s_waitcnt vmcnt(0)
	v_lshlrev_b32_e32 v6, 16, v0
	v_and_b32_e32 v10, 0xffff0000, v0
	v_lshlrev_b32_e32 v34, 16, v1
	v_and_b32_e32 v35, 0xffff0000, v1
	global_load_dwordx4 v[42:45], v[12:13], off
	global_load_dwordx2 v[0:1], v[12:13], off offset:16
	v_mul_f32_e32 v8, v10, v10
	v_fmac_f32_e32 v8, v6, v6
	v_fmac_f32_e32 v8, v34, v34
	v_lshlrev_b32_e32 v41, 16, v2
	v_fmac_f32_e32 v8, v35, v35
	v_and_b32_e32 v2, 0xffff0000, v2
	v_fmac_f32_e32 v8, v41, v41
	v_fmac_f32_e32 v8, v2, v2
	s_nop 1
	v_add_f32_dpp v8, v8, v8 quad_perm:[1,0,3,2] row_mask:0xf bank_mask:0xf bound_ctrl:1
	s_nop 1
	v_add_f32_dpp v8, v8, v8 quad_perm:[2,3,0,1] row_mask:0xf bank_mask:0xf bound_ctrl:1
	s_nop 1
	v_add_f32_dpp v8, v8, v8 row_half_mirror row_mask:0xf bank_mask:0xf bound_ctrl:1
	s_nop 1
	v_add_f32_dpp v8, v8, v8 row_mirror row_mask:0xf bank_mask:0xf bound_ctrl:1
	s_nop 0
	v_readlane_b32 s98, v8, 0
	v_readlane_b32 s99, v8, 16
	v_readlane_b32 s100, v8, 32
	v_readlane_b32 s101, v8, 48
	v_mov_b32_e32 v8, s98
	v_add_f32_e32 v8, s99, v8
	v_mov_b32_e32 v9, s100
	v_add_f32_e32 v9, s101, v9
	v_add_f32_e32 v8, v8, v9
	v_fmamk_f32 v8, v8, 0x3b2aaaab, v39
	v_mul_f32_e32 v9, 0x4f800000, v8
	v_cmp_gt_f32_e32 vcc, s24, v8
	s_nop 1
	v_cndmask_b32_e32 v46, v8, v9, vcc
	v_sqrt_f32_e32 v47, v46
	v_lshl_add_u64 v[8:9], s[50:51], 0, v[24:25]
	v_add_u32_e32 v48, -1, v47
	v_add_u32_e32 v49, 1, v47
	v_fma_f32 v50, -v48, v47, v46
	v_fma_f32 v51, -v49, v47, v46
	v_cmp_ge_f32_e64 s[0:1], 0, v50
	s_nop 1
	v_cndmask_b32_e64 v47, v47, v48, s[0:1]
	v_cmp_lt_f32_e64 s[0:1], 0, v51
	s_nop 1
	v_cndmask_b32_e64 v47, v47, v49, s[0:1]
	v_mul_f32_e32 v48, 0x37800000, v47
	v_cndmask_b32_e32 v47, v47, v48, vcc
	v_cmp_class_f32_e32 vcc, v46, v40
	s_nop 1
	v_cndmask_b32_e32 v46, v47, v46, vcc
	v_div_scale_f32 v47, s[0:1], v46, v46, 1.0
	v_rcp_f32_e32 v48, v47
	v_add_co_u32_e32 v8, vcc, s3, v8
	v_fma_f32 v50, -v47, v48, 1.0
	s_nop 0
	v_addc_co_u32_e32 v9, vcc, 0, v9, vcc
	v_div_scale_f32 v49, vcc, 1.0, v46, 1.0
	v_fmac_f32_e32 v48, v50, v48
	v_mul_f32_e32 v50, v49, v48
	v_fma_f32 v51, -v47, v50, v49
	v_fmac_f32_e32 v50, v51, v48
	v_fma_f32 v47, -v47, v50, v49
	v_div_fmas_f32 v47, v47, v48, v50
	v_div_fixup_f32 v46, v47, v46, 1.0
	v_mul_f32_e32 v6, v46, v6
	v_mul_f32_e32 v10, v46, v10
	v_mul_f32_e32 v41, v46, v41
	v_mul_f32_e32 v2, v46, v2
	v_mul_f32_e32 v34, v46, v34
	v_mul_f32_e32 v35, v46, v35
	s_waitcnt vmcnt(1)
	v_mul_f32_e32 v6, v42, v6
	v_mul_f32_e32 v10, v43, v10
	s_waitcnt vmcnt(0)
	v_mul_f32_e32 v0, v0, v41
	v_mul_f32_e32 v1, v1, v2
	v_cvt_pk_bf16_f32 v2, v6, v10
	v_mul_f32_e32 v34, v44, v34
	v_mul_f32_e32 v35, v45, v35
	global_store_dword v[4:5], v2, off
	v_cvt_pk_bf16_f32 v2, v34, v35
	global_store_dword v[4:5], v2, off offset:4
	v_cvt_pk_bf16_f32 v0, v0, v1
	global_store_dword v[4:5], v0, off offset:8
	global_load_dwordx2 v[0:1], v[8:9], off offset:768
	s_nop 0
	global_load_dwordx4 v[42:45], v[14:15], off
	s_waitcnt vmcnt(1)
	v_lshlrev_b32_e32 v2, 16, v0
	v_and_b32_e32 v0, 0xffff0000, v0
	v_mul_f32_e32 v5, v0, v0
	v_lshlrev_b32_e32 v4, 16, v1
	v_fmac_f32_e32 v5, v2, v2
	v_and_b32_e32 v1, 0xffff0000, v1
	v_fmac_f32_e32 v5, v4, v4
	v_fmac_f32_e32 v5, v1, v1
	s_nop 1
	v_add_f32_dpp v5, v5, v5 quad_perm:[1,0,3,2] row_mask:0xf bank_mask:0xf bound_ctrl:1
	s_nop 1
	v_add_f32_dpp v5, v5, v5 quad_perm:[2,3,0,1] row_mask:0xf bank_mask:0xf bound_ctrl:1
	s_nop 1
	v_add_f32_dpp v5, v5, v5 row_half_mirror row_mask:0xf bank_mask:0xf bound_ctrl:1
	s_nop 1
	v_add_f32_dpp v5, v5, v5 row_mirror row_mask:0xf bank_mask:0xf bound_ctrl:1
	s_nop 0
	v_readlane_b32 s98, v5, 0
	v_readlane_b32 s99, v5, 16
	v_readlane_b32 s100, v5, 32
	v_readlane_b32 s101, v5, 48
	v_mov_b32_e32 v5, s98
	v_add_f32_e32 v5, s99, v5
	v_mov_b32_e32 v6, s100
	v_add_f32_e32 v6, s101, v6
	v_add_f32_e32 v5, v5, v6
	v_fmamk_f32 v5, v5, 0x3b800000, v39
	v_mul_f32_e32 v6, 0x4f800000, v5
	v_cmp_gt_f32_e32 vcc, s24, v5
	s_nop 1
	v_cndmask_b32_e32 v5, v5, v6, vcc
	v_sqrt_f32_e32 v6, v5
	s_nop 0
	v_add_u32_e32 v10, -1, v6
	v_add_u32_e32 v34, 1, v6
	v_fma_f32 v35, -v10, v6, v5
	v_fma_f32 v41, -v34, v6, v5
	v_cmp_ge_f32_e64 s[0:1], 0, v35
	s_nop 1
	v_cndmask_b32_e64 v6, v6, v10, s[0:1]
	v_cmp_lt_f32_e64 s[0:1], 0, v41
	s_nop 1
	v_cndmask_b32_e64 v6, v6, v34, s[0:1]
	v_mul_f32_e32 v10, 0x37800000, v6
	v_cndmask_b32_e32 v6, v6, v10, vcc
	v_cmp_class_f32_e32 vcc, v5, v40
	s_nop 1
	v_cndmask_b32_e32 v5, v6, v5, vcc
	v_div_scale_f32 v6, s[0:1], v5, v5, 1.0
	v_rcp_f32_e32 v10, v6
	v_div_scale_f32 v34, vcc, 1.0, v5, 1.0
	v_fma_f32 v35, -v6, v10, 1.0
	v_fmac_f32_e32 v10, v35, v10
	v_mul_f32_e32 v35, v34, v10
	v_fma_f32 v41, -v6, v35, v34
	v_fmac_f32_e32 v35, v41, v10
	v_fma_f32 v6, -v6, v35, v34
	v_div_fmas_f32 v6, v6, v10, v35
	v_div_fixup_f32 v5, v6, v5, 1.0
	v_mul_f32_e32 v0, v5, v0
	v_mul_f32_e32 v2, v5, v2
	s_waitcnt vmcnt(0)
	v_mul_f32_e32 v0, v43, v0
	v_mul_f32_e32 v4, v5, v4
	v_mul_f32_e32 v1, v5, v1
	v_mul_f32_e32 v2, v42, v2
	v_cvt_pk_bf16_f32 v0, v2, v0
	v_mul_f32_e32 v4, v44, v4
	v_mul_f32_e32 v1, v45, v1
	global_store_dword v[8:9], v0, off offset:768
	v_cvt_pk_bf16_f32 v0, v4, v1
	global_store_dword v[8:9], v0, off offset:772
	s_and_saveexec_b64 s[0:1], s[4:5]
	s_xor_b64 s[0:1], exec, s[0:1]
	s_and_b32 s14, s26, 0x1fff
	s_add_i32 s15, s26, 0xffff8000
	s_or_saveexec_b64 s[0:1], s[0:1]
	v_mov_b32_e32 v4, s15
	v_mov_b32_e32 v5, s14
	s_xor_b64 exec, exec, s[0:1]
	s_cbranch_execz .LBB0_423
; __device__ __forceinline__ unsigned pkbf(float lo, float hi) { return pg8::cvt_pk_bf16(lo, hi); }
; __device__ __forceinline__ void p5_row(const P& p, int row, int lane) {
;     ...
;     if (lane < 16) { const float x1 = __uint_as_float((unsigned)za[640 + lane] << 16), x2 = __uint_as_float((unsigned)za[656 + lane] << 16);
;       const float* rp = (const float*)(ws + WS_ROPE) + ((size_t)seq_pos(row) * 16 + lane) * 2; const float c = rp[0], s = rp[1];
;       const unsigned w = pkbf(x1 * c - x2 * s, x1 * s + x2 * c);
;       unsigned* kr = (unsigned*)((bf16_t*)((unsigned char*)p.out + DO_K) + (size_t)row * 768 + 64) + lane;
; #pragma unroll
;       for (int h = 0; h < NH; ++h) kr[h * 48] = w; }
	s_and_b32 s27, s26, 0x1fff
	s_add_i32 s28, s26, 0xffff8000
	v_lshl_add_u64 v[0:1], s[50:51], 0, v[28:29]
	s_cmp_lt_i32 s26, 0x8000
	v_add_co_u32_e32 v0, vcc, 0x12000000, v0
	s_cselect_b32 s18, s27, s28
	s_nop 0
	v_addc_co_u32_e32 v1, vcc, 0, v1, vcc
	s_lshl_b64 s[14:15], s[18:19], 7
	v_lshl_add_u64 v[4:5], v[16:17], 0, s[14:15]
	global_load_ushort v2, v[0:1], off offset:1280
	global_load_ushort v6, v[0:1], off offset:1312
	s_nop 0
	global_load_dwordx2 v[0:1], v[4:5], off
	v_mov_b32_e32 v4, s28
	s_waitcnt vmcnt(2)
	v_lshlrev_b32_e32 v2, 16, v2
	s_waitcnt vmcnt(1)
	v_lshlrev_b32_e32 v5, 16, v6
	s_waitcnt vmcnt(0)
	v_mul_f32_e32 v6, v1, v5
	v_mul_f32_e32 v5, v0, v5
	v_fma_f32 v0, v0, v2, -v6
	v_fmac_f32_e32 v5, v1, v2
	v_cvt_pk_bf16_f32 v0, v0, v5
	v_mov_b32_e32 v5, s27
	global_store_dword v[30:31], v0, off
	global_store_dword v[30:31], v0, off offset:192
	global_store_dword v[30:31], v0, off offset:384
	global_store_dword v[30:31], v0, off offset:576
	global_store_dword v[30:31], v0, off offset:768
	global_store_dword v[30:31], v0, off offset:960
	global_store_dword v[30:31], v0, off offset:1152
	global_store_dword v[30:31], v0, off offset:1344
